# v026 + attention block loop: next block's K/V/Q global loads issued right after this block's ds_writes are issued, before the lgkmcnt(0) wait and workgroup barrier (phase is bound by the load skeleton
# baseline (speedup 1.0000x reference)
; #define ATT_LOADKV(dst, nn) do { const bf16* src_ = qcol + (rowbase + (size_t)(128 * (nn) + srow) * dil) * NQKV + 1024 + sch * 8; const size_t st_ = (size_t)32 * dil * NQKV; \
;         _Pragma("unroll") for (int i_ = 0; i_ < 4; ++i_) { dst[i_] = __builtin_nontemporal_load((const v4u*)(src_ + i_ * st_)); dst[4 + i_] = __builtin_nontemporal_load((const v4u*)(src_ + i_ * st_ + 1024)); } } while (0)
; #define ATT_LOADQ(nn) do { const bf16* src_ = qcol + (rowbase + (size_t)(128 * (nn) + 16 * w + lq) * dil) * NQKV + 8 * gq; \
;         _Pragma("unroll") for (int s_ = 0; s_ < 4; ++s_) qn[s_] = __builtin_nontemporal_load((const bf16x8*)(src_ + 32 * s_)); } while (0)
; #define ATT_WRITEKV(slot) do { LAS unsigned char* dk_ = lds + (slot) * SLOTB + sdst; LAS unsigned char* dv_ = lds + (slot) * SLOTB + sdstv; \
;         _Pragma("unroll") for (int i_ = 0; i_ < 4; ++i_) { *(LAS v4u*)(dk_ + 8192 * i_) = kv[i_]; *(LAS v4u*)(dv_ + 8192 * i_) = kv[4 + i_]; } } while (0)
; __device__ __forceinline__ void segment(LAS unsigned char* lds, const bf16* __restrict__ QKV, bf16* __restrict__ Og, float* __restrict__ L2, int bl, int g, int h, int r, int dil, int n0, int cnt, int tid) {
;     ...
;     for (int n = n0; n < n0 + cnt; ++n) {
;         ATT_WRITEKV(n & 1);
; #pragma unroll
;         for (int s = 0; s < 4; ++s) qf[s] = qn[s];
;         __syncthreads();
;         if (n + 1 < n0 + cnt) { ATT_LOADKV(kv, n + 1); ATT_LOADQ(n + 1); }
.LBB0_296:
	s_add_i32 s22, s37, -1
	s_and_b32 s51, s22, 1
	s_lshl_b32 s55, s51, 15
	s_add_i32 s39, s55, 0
	s_cmp_ge_u32 s37, s33
	s_cselect_b64 s[22:23], -1, 0
	v_add_u32_e32 v0, s39, v127
	s_and_b64 vcc, exec, s[22:23]
	v_add_u32_e32 v1, s39, v136
	ds_write_b128 v0, v[4:7]
	ds_write_b128 v1, v[8:11]
	ds_write_b128 v0, v[12:15] offset:8192
	ds_write_b128 v1, v[16:19] offset:8192
	ds_write_b128 v0, v[20:23] offset:16384
	ds_write_b128 v1, v[24:27] offset:16384
	ds_write_b128 v0, v[28:31] offset:24576
	ds_write_b128 v1, v[32:35] offset:24576
	s_nop 1
	s_cbranch_vccnz .Lnoload_P2
	v_lshl_add_u64 v[0:1], v[112:113], 0, s[56:57]
	v_add_co_u32_e32 v4, vcc, 0x7c00000, v0
	s_nop 1
	v_addc_co_u32_e32 v5, vcc, 0, v1, vcc
	v_add_co_u32_e32 v0, vcc, 0x7c01000, v0
	s_nop 1
	v_addc_co_u32_e32 v1, vcc, 0, v1, vcc
	global_load_dwordx4 v[4:7], v[4:5], off offset:2048 nt
	s_nop 0
	global_load_dwordx4 v[8:11], v[0:1], off nt
	v_lshl_add_u64 v[0:1], v[114:115], 0, s[56:57]
	v_add_co_u32_e32 v12, vcc, 0x7c00000, v0
	s_nop 1
	v_addc_co_u32_e32 v13, vcc, 0, v1, vcc
	v_add_co_u32_e32 v0, vcc, 0x7c01000, v0
	s_nop 1
	v_addc_co_u32_e32 v1, vcc, 0, v1, vcc
	global_load_dwordx4 v[12:15], v[12:13], off offset:2048 nt
	s_nop 0
	global_load_dwordx4 v[16:19], v[0:1], off nt
	v_lshl_add_u64 v[0:1], v[110:111], 0, s[56:57]
	v_add_co_u32_e32 v20, vcc, 0x7c00000, v0
	s_nop 1
	v_addc_co_u32_e32 v21, vcc, 0, v1, vcc
	v_add_co_u32_e32 v0, vcc, 0x7c01000, v0
	s_nop 1
	v_addc_co_u32_e32 v1, vcc, 0, v1, vcc
	global_load_dwordx4 v[20:23], v[20:21], off offset:2048 nt
	s_nop 0
	global_load_dwordx4 v[24:27], v[0:1], off nt
	v_lshl_add_u64 v[0:1], v[108:109], 0, s[56:57]
	v_add_co_u32_e32 v28, vcc, 0x7c00000, v0
	s_nop 1
	v_addc_co_u32_e32 v29, vcc, 0, v1, vcc
	v_add_co_u32_e32 v0, vcc, 0x7c01000, v0
	s_nop 1
	v_addc_co_u32_e32 v1, vcc, 0, v1, vcc
	global_load_dwordx4 v[28:31], v[28:29], off offset:2048 nt
	s_nop 0
	global_load_dwordx4 v[32:35], v[0:1], off nt
	v_lshl_add_u64 v[0:1], v[116:117], 0, v[106:107]
	global_load_dwordx4 v[36:39], v[0:1], off nt
	global_load_dwordx4 v[40:43], v[0:1], off offset:64 nt
	global_load_dwordx4 v[44:47], v[0:1], off offset:128 nt
	global_load_dwordx4 v[48:51], v[0:1], off offset:192 nt
.Lnoload_P2:
	s_waitcnt lgkmcnt(0)
	s_barrier
